# EpiGU packed f32 multiplies/fma replaced by scalar pairs (de-packed), otherwise v027
# baseline (speedup 1.0000x reference)
.LBB0_82:
	s_lshl_b32 s0, s54, 8
	s_add_i32 s0, s0, s65
	s_lshl_b32 s26, s53, 7
	v_and_or_b32 v140, v218, 15, s0
	v_ashrrev_i32_e32 v141, 31, v140
	v_lshl_add_u64 v[142:143], v[140:141], 3, s[10:11]
	global_load_dwordx2 v[146:147], v[142:143], off
	global_load_dwordx2 v[148:149], v[142:143], off offset:128
	global_load_dwordx2 v[150:151], v[142:143], off offset:256
	global_load_dwordx2 v[152:153], v[142:143], off offset:384
	global_load_dwordx2 v[154:155], v[142:143], off offset:1024
	global_load_dwordx2 v[156:157], v[142:143], off offset:1152
	global_load_dwordx2 v[158:159], v[142:143], off offset:1280
	global_load_dwordx2 v[160:161], v[142:143], off offset:1408
	s_ashr_i32 s27, s26, 31
	s_movk_i32 s13, 0x1600
	s_lshl_b64 s[26:27], s[26:27], 1
	v_and_b32_e32 v184, 48, v218
	s_andn2_b64 vcc, exec, s[4:5]
	v_mov_b64_e32 v[196:197], s[90:91]
	v_mad_i64_i32 v[190:191], s[0:1], v140, s13, v[196:197]
	v_lshl_add_u64 v[190:191], v[190:191], 0, s[26:27]
	v_lshl_add_u64 v[190:191], v[190:191], 0, s[88:89]
	v_lshl_add_u64 v[190:191], v[190:191], 0, v[184:185]
	v_mov_b32_e32 v178, 0xbfb8aa3b
	v_mov_b32_e32 v180, 1.0
	s_waitcnt vmcnt(0)
	v_ffbh_u32_e32 v162, v147
	v_ffbh_u32_e32 v164, v149
	v_ffbh_u32_e32 v166, v151
	v_ffbh_u32_e32 v168, v153
	v_ffbh_u32_e32 v170, v155
	v_ffbh_u32_e32 v172, v157
	v_ffbh_u32_e32 v174, v159
	v_ffbh_u32_e32 v176, v161
	v_min_u32_e32 v162, 32, v162
	v_min_u32_e32 v164, 32, v164
	v_min_u32_e32 v166, 32, v166
	v_min_u32_e32 v168, 32, v168
	v_min_u32_e32 v170, 32, v170
	v_min_u32_e32 v172, 32, v172
	v_min_u32_e32 v174, 32, v174
	v_min_u32_e32 v176, 32, v176
	v_lshlrev_b64 v[146:147], v162, v[146:147]
	v_lshlrev_b64 v[148:149], v164, v[148:149]
	v_lshlrev_b64 v[150:151], v166, v[150:151]
	v_lshlrev_b64 v[152:153], v168, v[152:153]
	v_lshlrev_b64 v[154:155], v170, v[154:155]
	v_lshlrev_b64 v[156:157], v172, v[156:157]
	v_lshlrev_b64 v[158:159], v174, v[158:159]
	v_lshlrev_b64 v[160:161], v176, v[160:161]
	v_min_u32_e32 v146, 1, v146
	v_min_u32_e32 v148, 1, v148
	v_min_u32_e32 v150, 1, v150
	v_min_u32_e32 v152, 1, v152
	v_min_u32_e32 v154, 1, v154
	v_min_u32_e32 v156, 1, v156
	v_min_u32_e32 v158, 1, v158
	v_min_u32_e32 v160, 1, v160
	v_or_b32_e32 v146, v147, v146
	v_or_b32_e32 v148, v149, v148
	v_or_b32_e32 v150, v151, v150
	v_or_b32_e32 v152, v153, v152
	v_or_b32_e32 v154, v155, v154
	v_or_b32_e32 v156, v157, v156
	v_or_b32_e32 v158, v159, v158
	v_or_b32_e32 v160, v161, v160
	v_cvt_f32_u32_e32 v146, v146
	v_cvt_f32_u32_e32 v148, v148
	v_cvt_f32_u32_e32 v150, v150
	v_cvt_f32_u32_e32 v152, v152
	v_cvt_f32_u32_e32 v154, v154
	v_cvt_f32_u32_e32 v156, v156
	v_cvt_f32_u32_e32 v158, v158
	v_cvt_f32_u32_e32 v160, v160
	v_sub_u32_e32 v162, 32, v162
	v_sub_u32_e32 v164, 32, v164
	v_sub_u32_e32 v166, 32, v166
	v_sub_u32_e32 v168, 32, v168
	v_sub_u32_e32 v170, 32, v170
	v_sub_u32_e32 v172, 32, v172
	v_sub_u32_e32 v174, 32, v174
	v_sub_u32_e32 v176, 32, v176
	v_ldexp_f32 v162, v146, v162
	v_ldexp_f32 v164, v148, v164
	v_ldexp_f32 v166, v150, v166
	v_ldexp_f32 v168, v152, v168
	v_ldexp_f32 v170, v154, v170
	v_ldexp_f32 v172, v156, v172
	v_ldexp_f32 v174, v158, v174
	v_ldexp_f32 v176, v160, v176
	v_mul_f32_e32 v162, 0x33800000, v162
	v_mul_f32_e32 v164, 0x33800000, v164
	v_mul_f32_e32 v166, 0x33800000, v166
	v_mul_f32_e32 v168, 0x33800000, v168
	v_mul_f32_e32 v170, 0x33800000, v170
	v_mul_f32_e32 v172, 0x33800000, v172
	v_mul_f32_e32 v174, 0x33800000, v174
	v_mul_f32_e32 v176, 0x33800000, v176
	v_fmamk_f32 v162, v162, 0x3a800000, v219
	v_fmamk_f32 v164, v164, 0x3a800000, v219
	v_fmamk_f32 v166, v166, 0x3a800000, v219
	v_fmamk_f32 v168, v168, 0x3a800000, v219
	v_fmamk_f32 v170, v170, 0x3a800000, v219
	v_fmamk_f32 v172, v172, 0x3a800000, v219
	v_fmamk_f32 v174, v174, 0x3a800000, v219
	v_fmamk_f32 v176, v176, 0x3a800000, v219
	v_rsq_f32_e32 v236, v162
	v_rsq_f32_e32 v238, v164
	v_rsq_f32_e32 v240, v166
	v_rsq_f32_e32 v242, v168
	v_rsq_f32_e32 v244, v170
	v_rsq_f32_e32 v246, v172
	v_rsq_f32_e32 v248, v174
	v_rsq_f32_e32 v250, v176
	v_mul_f32_e32 v236, 0xbfb8aa3b, v236
	v_mul_f32_e32 v238, 0xbfb8aa3b, v238
	v_mul_f32_e32 v240, 0xbfb8aa3b, v240
	v_mul_f32_e32 v242, 0xbfb8aa3b, v242
	v_mul_f32_e32 v244, 0xbfb8aa3b, v244
	v_mul_f32_e32 v246, 0xbfb8aa3b, v246
	v_mul_f32_e32 v248, 0xbfb8aa3b, v248
	v_mul_f32_e32 v250, 0xbfb8aa3b, v250
	v_mul_f32_e32 v146, v124, v236
	v_mul_f32_e32 v147, v125, v236
	v_mul_f32_e32 v148, v126, v236
	v_mul_f32_e32 v149, v127, v236
	v_mul_f32_e32 v150, v116, v236
	v_mul_f32_e32 v151, v117, v236
	v_mul_f32_e32 v152, v118, v236
	v_mul_f32_e32 v153, v119, v236
	v_exp_f32_e32 v146, v146
	v_exp_f32_e32 v147, v147
	v_exp_f32_e32 v148, v148
	v_exp_f32_e32 v149, v149
	v_exp_f32_e32 v150, v150
	v_exp_f32_e32 v151, v151
	v_exp_f32_e32 v152, v152
	v_exp_f32_e32 v153, v153
	v_mul_f32_e32 v120, v124, v120
	v_mul_f32_e32 v121, v125, v121
	v_mul_f32_e32 v122, v126, v122
	v_mul_f32_e32 v123, v127, v123
	v_mul_f32_e32 v112, v116, v112
	v_mul_f32_e32 v113, v117, v113
	v_mul_f32_e32 v114, v118, v114
	v_mul_f32_e32 v115, v119, v115
	v_fma_f32 v146, v146, v162, v162
	v_fma_f32 v147, v147, v162, v162
	v_fma_f32 v148, v148, v162, v162
	v_fma_f32 v149, v149, v162, v162
	v_fma_f32 v150, v150, v162, v162
	v_fma_f32 v151, v151, v162, v162
	v_fma_f32 v152, v152, v162, v162
	v_fma_f32 v153, v153, v162, v162
	v_rcp_f32_e32 v146, v146
	v_rcp_f32_e32 v147, v147
	v_rcp_f32_e32 v148, v148
	v_rcp_f32_e32 v149, v149
	v_rcp_f32_e32 v150, v150
	v_rcp_f32_e32 v151, v151
	v_rcp_f32_e32 v152, v152
	v_rcp_f32_e32 v153, v153
	v_mul_f32_e32 v124, v120, v146
	v_mul_f32_e32 v125, v121, v147
	v_mul_f32_e32 v126, v122, v148
	v_mul_f32_e32 v127, v123, v149
	v_mul_f32_e32 v116, v112, v150
	v_mul_f32_e32 v117, v113, v151
	v_mul_f32_e32 v118, v114, v152
	v_mul_f32_e32 v119, v115, v153
	v_cvt_pk_bf16_f32 v202, v124, v125
	v_cvt_pk_bf16_f32 v203, v126, v127
	v_cvt_pk_bf16_f32 v204, v116, v117
	v_cvt_pk_bf16_f32 v205, v118, v119
	global_store_dwordx4 v[190:191], v[202:205], off
	s_mov_b64 s[0:1], 0x16000
	v_lshl_add_u64 v[194:195], v[190:191], 0, s[0:1]
	v_mul_f32_e32 v146, v108, v238
	v_mul_f32_e32 v147, v109, v238
	v_mul_f32_e32 v148, v110, v238
	v_mul_f32_e32 v149, v111, v238
	v_mul_f32_e32 v150, v100, v238
	v_mul_f32_e32 v151, v101, v238
	v_mul_f32_e32 v152, v102, v238
	v_mul_f32_e32 v153, v103, v238
	v_exp_f32_e32 v146, v146
	v_exp_f32_e32 v147, v147
	v_exp_f32_e32 v148, v148
	v_exp_f32_e32 v149, v149
	v_exp_f32_e32 v150, v150
	v_exp_f32_e32 v151, v151
	v_exp_f32_e32 v152, v152
	v_exp_f32_e32 v153, v153
	v_mul_f32_e32 v104, v108, v104
	v_mul_f32_e32 v105, v109, v105
	v_mul_f32_e32 v106, v110, v106
	v_mul_f32_e32 v107, v111, v107
	v_mul_f32_e32 v96, v100, v96
	v_mul_f32_e32 v97, v101, v97
	v_mul_f32_e32 v98, v102, v98
	v_mul_f32_e32 v99, v103, v99
	v_fma_f32 v146, v146, v164, v164
	v_fma_f32 v147, v147, v164, v164
	v_fma_f32 v148, v148, v164, v164
	v_fma_f32 v149, v149, v164, v164
	v_fma_f32 v150, v150, v164, v164
	v_fma_f32 v151, v151, v164, v164
	v_fma_f32 v152, v152, v164, v164
	v_fma_f32 v153, v153, v164, v164
	v_rcp_f32_e32 v146, v146
	v_rcp_f32_e32 v147, v147
	v_rcp_f32_e32 v148, v148
	v_rcp_f32_e32 v149, v149
	v_rcp_f32_e32 v150, v150
	v_rcp_f32_e32 v151, v151
	v_rcp_f32_e32 v152, v152
	v_rcp_f32_e32 v153, v153
	v_mul_f32_e32 v108, v104, v146
	v_mul_f32_e32 v109, v105, v147
	v_mul_f32_e32 v110, v106, v148
	v_mul_f32_e32 v111, v107, v149
	v_mul_f32_e32 v100, v96, v150
	v_mul_f32_e32 v101, v97, v151
	v_mul_f32_e32 v102, v98, v152
	v_mul_f32_e32 v103, v99, v153
	v_cvt_pk_bf16_f32 v206, v108, v109
	v_cvt_pk_bf16_f32 v207, v110, v111
	v_cvt_pk_bf16_f32 v208, v100, v101
	v_cvt_pk_bf16_f32 v209, v102, v103
	global_store_dwordx4 v[194:195], v[206:209], off
	s_mov_b64 s[0:1], 0x2c000
	v_lshl_add_u64 v[192:193], v[190:191], 0, s[0:1]
	v_mul_f32_e32 v146, v92, v240
	v_mul_f32_e32 v147, v93, v240
	v_mul_f32_e32 v148, v94, v240
	v_mul_f32_e32 v149, v95, v240
	v_mul_f32_e32 v150, v84, v240
	v_mul_f32_e32 v151, v85, v240
	v_mul_f32_e32 v152, v86, v240
	v_mul_f32_e32 v153, v87, v240
	v_exp_f32_e32 v146, v146
	v_exp_f32_e32 v147, v147
	v_exp_f32_e32 v148, v148
	v_exp_f32_e32 v149, v149
	v_exp_f32_e32 v150, v150
	v_exp_f32_e32 v151, v151
	v_exp_f32_e32 v152, v152
	v_exp_f32_e32 v153, v153
	v_mul_f32_e32 v88, v92, v88
	v_mul_f32_e32 v89, v93, v89
	v_mul_f32_e32 v90, v94, v90
	v_mul_f32_e32 v91, v95, v91
	v_mul_f32_e32 v80, v84, v80
	v_mul_f32_e32 v81, v85, v81
	v_mul_f32_e32 v82, v86, v82
	v_mul_f32_e32 v83, v87, v83
	v_fma_f32 v146, v146, v166, v166
	v_fma_f32 v147, v147, v166, v166
	v_fma_f32 v148, v148, v166, v166
	v_fma_f32 v149, v149, v166, v166
	v_fma_f32 v150, v150, v166, v166
	v_fma_f32 v151, v151, v166, v166
	v_fma_f32 v152, v152, v166, v166
	v_fma_f32 v153, v153, v166, v166
	v_rcp_f32_e32 v146, v146
	v_rcp_f32_e32 v147, v147
	v_rcp_f32_e32 v148, v148
	v_rcp_f32_e32 v149, v149
	v_rcp_f32_e32 v150, v150
	v_rcp_f32_e32 v151, v151
	v_rcp_f32_e32 v152, v152
	v_rcp_f32_e32 v153, v153
	v_mul_f32_e32 v92, v88, v146
	v_mul_f32_e32 v93, v89, v147
	v_mul_f32_e32 v94, v90, v148
	v_mul_f32_e32 v95, v91, v149
	v_mul_f32_e32 v84, v80, v150
	v_mul_f32_e32 v85, v81, v151
	v_mul_f32_e32 v86, v82, v152
	v_mul_f32_e32 v87, v83, v153
	v_cvt_pk_bf16_f32 v210, v92, v93
	v_cvt_pk_bf16_f32 v211, v94, v95
	v_cvt_pk_bf16_f32 v212, v84, v85
	v_cvt_pk_bf16_f32 v213, v86, v87
	global_store_dwordx4 v[192:193], v[210:213], off
	s_mov_b64 s[0:1], 0x42000
	v_lshl_add_u64 v[194:195], v[190:191], 0, s[0:1]
	v_mul_f32_e32 v146, v76, v242
	v_mul_f32_e32 v147, v77, v242
	v_mul_f32_e32 v148, v78, v242
	v_mul_f32_e32 v149, v79, v242
	v_mul_f32_e32 v150, v68, v242
	v_mul_f32_e32 v151, v69, v242
	v_mul_f32_e32 v152, v70, v242
	v_mul_f32_e32 v153, v71, v242
	v_exp_f32_e32 v146, v146
	v_exp_f32_e32 v147, v147
	v_exp_f32_e32 v148, v148
	v_exp_f32_e32 v149, v149
	v_exp_f32_e32 v150, v150
	v_exp_f32_e32 v151, v151
	v_exp_f32_e32 v152, v152
	v_exp_f32_e32 v153, v153
	v_mul_f32_e32 v72, v76, v72
	v_mul_f32_e32 v73, v77, v73
	v_mul_f32_e32 v74, v78, v74
	v_mul_f32_e32 v75, v79, v75
	v_mul_f32_e32 v64, v68, v64
	v_mul_f32_e32 v65, v69, v65
	v_mul_f32_e32 v66, v70, v66
	v_mul_f32_e32 v67, v71, v67
	v_fma_f32 v146, v146, v168, v168
	v_fma_f32 v147, v147, v168, v168
	v_fma_f32 v148, v148, v168, v168
	v_fma_f32 v149, v149, v168, v168
	v_fma_f32 v150, v150, v168, v168
	v_fma_f32 v151, v151, v168, v168
	v_fma_f32 v152, v152, v168, v168
	v_fma_f32 v153, v153, v168, v168
	v_rcp_f32_e32 v146, v146
	v_rcp_f32_e32 v147, v147
	v_rcp_f32_e32 v148, v148
	v_rcp_f32_e32 v149, v149
	v_rcp_f32_e32 v150, v150
	v_rcp_f32_e32 v151, v151
	v_rcp_f32_e32 v152, v152
	v_rcp_f32_e32 v153, v153
	v_mul_f32_e32 v76, v72, v146
	v_mul_f32_e32 v77, v73, v147
	v_mul_f32_e32 v78, v74, v148
	v_mul_f32_e32 v79, v75, v149
	v_mul_f32_e32 v68, v64, v150
	v_mul_f32_e32 v69, v65, v151
	v_mul_f32_e32 v70, v66, v152
	v_mul_f32_e32 v71, v67, v153
	v_cvt_pk_bf16_f32 v214, v76, v77
	v_cvt_pk_bf16_f32 v215, v78, v79
	v_cvt_pk_bf16_f32 v216, v68, v69
	v_cvt_pk_bf16_f32 v217, v70, v71
	global_store_dwordx4 v[194:195], v[214:217], off
	s_mov_b64 s[0:1], 0xb0000
	v_lshl_add_u64 v[192:193], v[190:191], 0, s[0:1]
	v_mul_f32_e32 v146, v60, v244
	v_mul_f32_e32 v147, v61, v244
	v_mul_f32_e32 v148, v62, v244
	v_mul_f32_e32 v149, v63, v244
	v_mul_f32_e32 v150, v52, v244
	v_mul_f32_e32 v151, v53, v244
	v_mul_f32_e32 v152, v54, v244
	v_mul_f32_e32 v153, v55, v244
	v_exp_f32_e32 v146, v146
	v_exp_f32_e32 v147, v147
	v_exp_f32_e32 v148, v148
	v_exp_f32_e32 v149, v149
	v_exp_f32_e32 v150, v150
	v_exp_f32_e32 v151, v151
	v_exp_f32_e32 v152, v152
	v_exp_f32_e32 v153, v153
	v_mul_f32_e32 v56, v60, v56
	v_mul_f32_e32 v57, v61, v57
	v_mul_f32_e32 v58, v62, v58
	v_mul_f32_e32 v59, v63, v59
	v_mul_f32_e32 v48, v52, v48
	v_mul_f32_e32 v49, v53, v49
	v_mul_f32_e32 v50, v54, v50
	v_mul_f32_e32 v51, v55, v51
	v_fma_f32 v146, v146, v170, v170
	v_fma_f32 v147, v147, v170, v170
	v_fma_f32 v148, v148, v170, v170
	v_fma_f32 v149, v149, v170, v170
	v_fma_f32 v150, v150, v170, v170
	v_fma_f32 v151, v151, v170, v170
	v_fma_f32 v152, v152, v170, v170
	v_fma_f32 v153, v153, v170, v170
	v_rcp_f32_e32 v146, v146
	v_rcp_f32_e32 v147, v147
	v_rcp_f32_e32 v148, v148
	v_rcp_f32_e32 v149, v149
	v_rcp_f32_e32 v150, v150
	v_rcp_f32_e32 v151, v151
	v_rcp_f32_e32 v152, v152
	v_rcp_f32_e32 v153, v153
	v_mul_f32_e32 v60, v56, v146
	v_mul_f32_e32 v61, v57, v147
	v_mul_f32_e32 v62, v58, v148
	v_mul_f32_e32 v63, v59, v149
	v_mul_f32_e32 v52, v48, v150
	v_mul_f32_e32 v53, v49, v151
	v_mul_f32_e32 v54, v50, v152
	v_mul_f32_e32 v55, v51, v153
	v_cvt_pk_bf16_f32 v202, v60, v61
	v_cvt_pk_bf16_f32 v203, v62, v63
	v_cvt_pk_bf16_f32 v204, v52, v53
	v_cvt_pk_bf16_f32 v205, v54, v55
	global_store_dwordx4 v[192:193], v[202:205], off
	s_mov_b64 s[0:1], 0xc6000
	v_lshl_add_u64 v[194:195], v[190:191], 0, s[0:1]
	v_mul_f32_e32 v146, v44, v246
	v_mul_f32_e32 v147, v45, v246
	v_mul_f32_e32 v148, v46, v246
	v_mul_f32_e32 v149, v47, v246
	v_mul_f32_e32 v150, v36, v246
	v_mul_f32_e32 v151, v37, v246
	v_mul_f32_e32 v152, v38, v246
	v_mul_f32_e32 v153, v39, v246
	v_exp_f32_e32 v146, v146
	v_exp_f32_e32 v147, v147
	v_exp_f32_e32 v148, v148
	v_exp_f32_e32 v149, v149
	v_exp_f32_e32 v150, v150
	v_exp_f32_e32 v151, v151
	v_exp_f32_e32 v152, v152
	v_exp_f32_e32 v153, v153
	v_mul_f32_e32 v40, v44, v40
	v_mul_f32_e32 v41, v45, v41
	v_mul_f32_e32 v42, v46, v42
	v_mul_f32_e32 v43, v47, v43
	v_mul_f32_e32 v32, v36, v32
	v_mul_f32_e32 v33, v37, v33
	v_mul_f32_e32 v34, v38, v34
	v_mul_f32_e32 v35, v39, v35
	v_fma_f32 v146, v146, v172, v172
	v_fma_f32 v147, v147, v172, v172
	v_fma_f32 v148, v148, v172, v172
	v_fma_f32 v149, v149, v172, v172
	v_fma_f32 v150, v150, v172, v172
	v_fma_f32 v151, v151, v172, v172
	v_fma_f32 v152, v152, v172, v172
	v_fma_f32 v153, v153, v172, v172
	v_rcp_f32_e32 v146, v146
	v_rcp_f32_e32 v147, v147
	v_rcp_f32_e32 v148, v148
	v_rcp_f32_e32 v149, v149
	v_rcp_f32_e32 v150, v150
	v_rcp_f32_e32 v151, v151
	v_rcp_f32_e32 v152, v152
	v_rcp_f32_e32 v153, v153
	v_mul_f32_e32 v44, v40, v146
	v_mul_f32_e32 v45, v41, v147
	v_mul_f32_e32 v46, v42, v148
	v_mul_f32_e32 v47, v43, v149
	v_mul_f32_e32 v36, v32, v150
	v_mul_f32_e32 v37, v33, v151
	v_mul_f32_e32 v38, v34, v152
	v_mul_f32_e32 v39, v35, v153
	v_cvt_pk_bf16_f32 v206, v44, v45
	v_cvt_pk_bf16_f32 v207, v46, v47
	v_cvt_pk_bf16_f32 v208, v36, v37
	v_cvt_pk_bf16_f32 v209, v38, v39
	global_store_dwordx4 v[194:195], v[206:209], off
	s_mov_b64 s[0:1], 0xdc000
	v_lshl_add_u64 v[192:193], v[190:191], 0, s[0:1]
	v_mul_f32_e32 v146, v28, v248
	v_mul_f32_e32 v147, v29, v248
	v_mul_f32_e32 v148, v30, v248
	v_mul_f32_e32 v149, v31, v248
	v_mul_f32_e32 v150, v20, v248
	v_mul_f32_e32 v151, v21, v248
	v_mul_f32_e32 v152, v22, v248
	v_mul_f32_e32 v153, v23, v248
	v_exp_f32_e32 v146, v146
	v_exp_f32_e32 v147, v147
	v_exp_f32_e32 v148, v148
	v_exp_f32_e32 v149, v149
	v_exp_f32_e32 v150, v150
	v_exp_f32_e32 v151, v151
	v_exp_f32_e32 v152, v152
	v_exp_f32_e32 v153, v153
	v_mul_f32_e32 v24, v28, v24
	v_mul_f32_e32 v25, v29, v25
	v_mul_f32_e32 v26, v30, v26
	v_mul_f32_e32 v27, v31, v27
	v_mul_f32_e32 v16, v20, v16
	v_mul_f32_e32 v17, v21, v17
	v_mul_f32_e32 v18, v22, v18
	v_mul_f32_e32 v19, v23, v19
	v_fma_f32 v146, v146, v174, v174
	v_fma_f32 v147, v147, v174, v174
	v_fma_f32 v148, v148, v174, v174
	v_fma_f32 v149, v149, v174, v174
	v_fma_f32 v150, v150, v174, v174
	v_fma_f32 v151, v151, v174, v174
	v_fma_f32 v152, v152, v174, v174
	v_fma_f32 v153, v153, v174, v174
	v_rcp_f32_e32 v146, v146
	v_rcp_f32_e32 v147, v147
	v_rcp_f32_e32 v148, v148
	v_rcp_f32_e32 v149, v149
	v_rcp_f32_e32 v150, v150
	v_rcp_f32_e32 v151, v151
	v_rcp_f32_e32 v152, v152
	v_rcp_f32_e32 v153, v153
	v_mul_f32_e32 v28, v24, v146
	v_mul_f32_e32 v29, v25, v147
	v_mul_f32_e32 v30, v26, v148
	v_mul_f32_e32 v31, v27, v149
	v_mul_f32_e32 v20, v16, v150
	v_mul_f32_e32 v21, v17, v151
	v_mul_f32_e32 v22, v18, v152
	v_mul_f32_e32 v23, v19, v153
	v_cvt_pk_bf16_f32 v210, v28, v29
	v_cvt_pk_bf16_f32 v211, v30, v31
	v_cvt_pk_bf16_f32 v212, v20, v21
	v_cvt_pk_bf16_f32 v213, v22, v23
	global_store_dwordx4 v[192:193], v[210:213], off
	s_mov_b64 s[0:1], 0xf2000
	v_lshl_add_u64 v[194:195], v[190:191], 0, s[0:1]
	v_mul_f32_e32 v146, v12, v250
	v_mul_f32_e32 v147, v13, v250
	v_mul_f32_e32 v148, v14, v250
	v_mul_f32_e32 v149, v15, v250
	v_mul_f32_e32 v150, v4, v250
	v_mul_f32_e32 v151, v5, v250
	v_mul_f32_e32 v152, v6, v250
	v_mul_f32_e32 v153, v7, v250
	v_exp_f32_e32 v146, v146
	v_exp_f32_e32 v147, v147
	v_exp_f32_e32 v148, v148
	v_exp_f32_e32 v149, v149
	v_exp_f32_e32 v150, v150
	v_exp_f32_e32 v151, v151
	v_exp_f32_e32 v152, v152
	v_exp_f32_e32 v153, v153
	v_mul_f32_e32 v8, v12, v8
	v_mul_f32_e32 v9, v13, v9
	v_mul_f32_e32 v10, v14, v10
	v_mul_f32_e32 v11, v15, v11
	v_mul_f32_e32 v0, v4, v0
	v_mul_f32_e32 v1, v5, v1
	v_mul_f32_e32 v2, v6, v2
	v_mul_f32_e32 v3, v7, v3
	v_fma_f32 v146, v146, v176, v176
	v_fma_f32 v147, v147, v176, v176
	v_fma_f32 v148, v148, v176, v176
	v_fma_f32 v149, v149, v176, v176
	v_fma_f32 v150, v150, v176, v176
	v_fma_f32 v151, v151, v176, v176
	v_fma_f32 v152, v152, v176, v176
	v_fma_f32 v153, v153, v176, v176
	v_rcp_f32_e32 v146, v146
	v_rcp_f32_e32 v147, v147
	v_rcp_f32_e32 v148, v148
	v_rcp_f32_e32 v149, v149
	v_rcp_f32_e32 v150, v150
	v_rcp_f32_e32 v151, v151
	v_rcp_f32_e32 v152, v152
	v_rcp_f32_e32 v153, v153
	v_mul_f32_e32 v12, v8, v146
	v_mul_f32_e32 v13, v9, v147
	v_mul_f32_e32 v14, v10, v148
	v_mul_f32_e32 v15, v11, v149
	v_mul_f32_e32 v4, v0, v150
	v_mul_f32_e32 v5, v1, v151
	v_mul_f32_e32 v6, v2, v152
	v_mul_f32_e32 v7, v3, v153
	v_cvt_pk_bf16_f32 v214, v12, v13
	v_cvt_pk_bf16_f32 v215, v14, v15
	v_cvt_pk_bf16_f32 v216, v4, v5
	v_cvt_pk_bf16_f32 v217, v6, v7
	global_store_dwordx4 v[194:195], v[214:217], off
	s_mov_b64 s[0:1], -1
	s_cbranch_vccnz .LBB0_75
	s_andn2_b64 vcc, exec, s[2:3]
	s_cbranch_vccnz .LBB0_74
	s_barrier
	s_branch .LBB0_74
